# phase-1 hand-written epilogue with the cross-lane line pairing restored (whole 128-byte lines per store) while keeping one base address per tile + running scalar offset; on v092
# baseline (speedup 1.0000x reference)
.LBB0_178:
	ds_read_b128 v[148:151], v159
	ds_read_b128 v[152:155], v159 offset:1024
	ds_read_b128 v[164:167], v159 offset:2048
	ds_read_b128 v[168:171], v159 offset:3072
	s_add_u32 s52, s50, 0xfffc0080
	s_addc_u32 s53, s51, -1
	s_cmp_eq_u32 s92, 12
	s_cselect_b32 s55, s11, s53
	s_cselect_b32 s54, s13, s52
	s_cselect_b32 s53, s17, s91
	s_cselect_b32 s52, s43, s45
	v_lshl_add_u64 v[156:157], s[50:51], 0, v[140:141]
	s_add_i32 m0, s58, 0xc000
	ds_read_b128 v[172:175], v160
	ds_read_b128 v[176:179], v160 offset:1024
	ds_read_b128 v[180:183], v160 offset:2048
	ds_read_b128 v[184:187], v160 offset:3072
	ds_read_b128 v[188:191], v160 offset:4096
	ds_read_b128 v[196:199], v160 offset:5120
	ds_read_b128 v[200:203], v160 offset:6144
	ds_read_b128 v[204:207], v160 offset:7168
	global_load_lds_dwordx4 v[156:157], off
	v_lshl_add_u64 v[156:157], s[50:51], 0, v[142:143]
	s_add_i32 m0, s58, 0xe000
	s_nop 0
	global_load_lds_dwordx4 v[156:157], off
	s_waitcnt lgkmcnt(8)
	s_barrier
	s_waitcnt lgkmcnt(0)
	v_mfma_f32_16x16x32_bf16 v[124:127], v[148:151], v[172:175], v[124:127]
	v_mfma_f32_16x16x32_bf16 v[120:123], v[164:167], v[172:175], v[120:123]
	v_mfma_f32_16x16x32_bf16 v[108:111], v[148:151], v[180:183], v[108:111]
	v_mfma_f32_16x16x32_bf16 v[104:107], v[164:167], v[180:183], v[104:107]
	v_mfma_f32_16x16x32_bf16 v[92:95], v[148:151], v[188:191], v[92:95]
	v_mfma_f32_16x16x32_bf16 v[88:91], v[164:167], v[188:191], v[88:91]
	v_mfma_f32_16x16x32_bf16 v[76:79], v[148:151], v[200:203], v[76:79]
	v_mfma_f32_16x16x32_bf16 v[72:75], v[164:167], v[200:203], v[72:75]
	v_mfma_f32_16x16x32_bf16 v[124:127], v[152:155], v[176:179], v[124:127]
	v_mfma_f32_16x16x32_bf16 v[120:123], v[168:171], v[176:179], v[120:123]
	v_mfma_f32_16x16x32_bf16 v[108:111], v[152:155], v[184:187], v[108:111]
	v_mfma_f32_16x16x32_bf16 v[104:107], v[168:171], v[184:187], v[104:107]
	v_mfma_f32_16x16x32_bf16 v[92:95], v[152:155], v[196:199], v[92:95]
	v_mfma_f32_16x16x32_bf16 v[88:91], v[168:171], v[196:199], v[88:91]
	v_mfma_f32_16x16x32_bf16 v[76:79], v[152:155], v[204:207], v[76:79]
	v_mfma_f32_16x16x32_bf16 v[72:75], v[168:171], v[204:207], v[72:75]
	s_barrier
	s_add_i32 s93, s89, s57
	v_lshl_add_u64 v[156:157], s[52:53], 0, v[130:131]
	s_mov_b32 m0, s93
	ds_read_b128 v[208:211], v161
	ds_read_b128 v[212:215], v161 offset:1024
	ds_read_b128 v[216:219], v161 offset:2048
	ds_read_b128 v[220:223], v161 offset:3072
	global_load_lds_dwordx4 v[156:157], off
	v_lshl_add_u64 v[224:225], s[52:53], 0, v[134:135]
	s_add_i32 m0, s93, 0x2000
	s_nop 0
	global_load_lds_dwordx4 v[224:225], off
	s_barrier
	s_waitcnt lgkmcnt(0)
	v_mfma_f32_16x16x32_bf16 v[116:119], v[208:211], v[172:175], v[116:119]
	v_mfma_f32_16x16x32_bf16 v[112:115], v[216:219], v[172:175], v[112:115]
	v_mfma_f32_16x16x32_bf16 v[100:103], v[208:211], v[180:183], v[100:103]
	v_mfma_f32_16x16x32_bf16 v[96:99], v[216:219], v[180:183], v[96:99]
	v_mfma_f32_16x16x32_bf16 v[84:87], v[208:211], v[188:191], v[84:87]
	v_mfma_f32_16x16x32_bf16 v[80:83], v[216:219], v[188:191], v[80:83]
	v_mfma_f32_16x16x32_bf16 v[68:71], v[208:211], v[200:203], v[68:71]
	v_mfma_f32_16x16x32_bf16 v[64:67], v[216:219], v[200:203], v[64:67]
	v_mfma_f32_16x16x32_bf16 v[116:119], v[212:215], v[176:179], v[116:119]
	v_mfma_f32_16x16x32_bf16 v[112:115], v[220:223], v[176:179], v[112:115]
	v_mfma_f32_16x16x32_bf16 v[100:103], v[212:215], v[184:187], v[100:103]
	v_mfma_f32_16x16x32_bf16 v[96:99], v[220:223], v[184:187], v[96:99]
	v_mfma_f32_16x16x32_bf16 v[84:87], v[212:215], v[196:199], v[84:87]
	v_mfma_f32_16x16x32_bf16 v[80:83], v[220:223], v[196:199], v[80:83]
	v_mfma_f32_16x16x32_bf16 v[68:71], v[212:215], v[204:207], v[68:71]
	v_mfma_f32_16x16x32_bf16 v[64:67], v[220:223], v[204:207], v[64:67]
	s_mov_b32 m0, s58
	v_lshl_add_u64 v[226:227], s[54:55], 0, v[128:129]
	s_barrier
	ds_read_b128 v[172:175], v160 offset:16384
	ds_read_b128 v[176:179], v160 offset:17408
	ds_read_b128 v[180:183], v160 offset:18432
	ds_read_b128 v[184:187], v160 offset:19456
	ds_read_b128 v[188:191], v160 offset:20480
	ds_read_b128 v[196:199], v160 offset:21504
	ds_read_b128 v[200:203], v160 offset:22528
	ds_read_b128 v[204:207], v160 offset:23552
	global_load_lds_dwordx4 v[226:227], off
	v_lshl_add_u64 v[228:229], s[54:55], 0, v[132:133]
	s_mov_b32 m0, s59
	s_nop 0
	global_load_lds_dwordx4 v[228:229], off
	s_barrier
	s_waitcnt lgkmcnt(0)
	v_mfma_f32_16x16x32_bf16 v[60:63], v[148:151], v[172:175], v[60:63]
	v_mfma_f32_16x16x32_bf16 v[56:59], v[164:167], v[172:175], v[56:59]
	v_mfma_f32_16x16x32_bf16 v[44:47], v[148:151], v[180:183], v[44:47]
	v_mfma_f32_16x16x32_bf16 v[40:43], v[164:167], v[180:183], v[40:43]
	v_mfma_f32_16x16x32_bf16 v[28:31], v[148:151], v[188:191], v[28:31]
	v_mfma_f32_16x16x32_bf16 v[24:27], v[164:167], v[188:191], v[24:27]
	v_mfma_f32_16x16x32_bf16 v[12:15], v[148:151], v[200:203], v[12:15]
	v_mfma_f32_16x16x32_bf16 v[8:11], v[164:167], v[200:203], v[8:11]
	v_mfma_f32_16x16x32_bf16 v[60:63], v[152:155], v[176:179], v[60:63]
	v_mfma_f32_16x16x32_bf16 v[56:59], v[168:171], v[176:179], v[56:59]
	v_mfma_f32_16x16x32_bf16 v[44:47], v[152:155], v[184:187], v[44:47]
	v_mfma_f32_16x16x32_bf16 v[40:43], v[168:171], v[184:187], v[40:43]
	v_mfma_f32_16x16x32_bf16 v[28:31], v[152:155], v[196:199], v[28:31]
	v_mfma_f32_16x16x32_bf16 v[24:27], v[168:171], v[196:199], v[24:27]
	v_mfma_f32_16x16x32_bf16 v[12:15], v[152:155], v[204:207], v[12:15]
	v_mfma_f32_16x16x32_bf16 v[8:11], v[168:171], v[204:207], v[8:11]
	s_barrier
	s_add_u32 s94, s52, 0x10000
	s_addc_u32 s95, s53, 0
	s_add_i32 s93, s90, s57
	v_lshl_add_u64 v[148:149], s[94:95], 0, v[130:131]
	s_mov_b32 m0, s93
	s_nop 0
	global_load_lds_dwordx4 v[148:149], off
	v_lshl_add_u64 v[148:149], s[94:95], 0, v[134:135]
	s_add_i32 m0, s93, 0x2000
	s_nop 0
	global_load_lds_dwordx4 v[148:149], off
	s_waitcnt vmcnt(6)
	s_barrier
	v_mfma_f32_16x16x32_bf16 v[52:55], v[208:211], v[172:175], v[52:55]
	v_mfma_f32_16x16x32_bf16 v[48:51], v[216:219], v[172:175], v[48:51]
	v_mfma_f32_16x16x32_bf16 v[36:39], v[208:211], v[180:183], v[36:39]
	v_mfma_f32_16x16x32_bf16 v[32:35], v[216:219], v[180:183], v[32:35]
	v_mfma_f32_16x16x32_bf16 v[20:23], v[208:211], v[188:191], v[20:23]
	v_mfma_f32_16x16x32_bf16 v[16:19], v[216:219], v[188:191], v[16:19]
	v_mfma_f32_16x16x32_bf16 v[4:7], v[208:211], v[200:203], v[4:7]
	v_mfma_f32_16x16x32_bf16 v[0:3], v[216:219], v[200:203], v[0:3]
	v_mfma_f32_16x16x32_bf16 v[52:55], v[212:215], v[176:179], v[52:55]
	v_mfma_f32_16x16x32_bf16 v[48:51], v[220:223], v[176:179], v[48:51]
	v_mfma_f32_16x16x32_bf16 v[36:39], v[212:215], v[184:187], v[36:39]
	v_mfma_f32_16x16x32_bf16 v[32:35], v[220:223], v[184:187], v[32:35]
	v_mfma_f32_16x16x32_bf16 v[20:23], v[212:215], v[196:199], v[20:23]
	v_mfma_f32_16x16x32_bf16 v[16:19], v[220:223], v[196:199], v[16:19]
	v_mfma_f32_16x16x32_bf16 v[4:7], v[212:215], v[204:207], v[4:7]
	v_mfma_f32_16x16x32_bf16 v[0:3], v[220:223], v[204:207], v[0:3]
	s_add_i32 s93, 0, 0x18000
	v_add_u32_e32 v136, s93, v158
	s_barrier
	ds_read_b128 v[148:151], v136
	ds_read_b128 v[152:155], v136 offset:1024
	ds_read_b128 v[164:167], v136 offset:2048
	ds_read_b128 v[168:171], v136 offset:3072
	s_add_u32 s54, s54, 0x40000
	s_addc_u32 s55, s55, 0
	s_mov_b32 m0, s60
	v_lshl_add_u64 v[208:209], s[54:55], 0, v[128:129]
	ds_read_b128 v[172:175], v160 offset:32768
	ds_read_b128 v[176:179], v160 offset:33792
	ds_read_b128 v[180:183], v160 offset:34816
	ds_read_b128 v[184:187], v160 offset:35840
	ds_read_b128 v[188:191], v160 offset:36864
	ds_read_b128 v[196:199], v160 offset:37888
	ds_read_b128 v[200:203], v160 offset:38912
	ds_read_b128 v[204:207], v160 offset:39936
	global_load_lds_dwordx4 v[208:209], off
	v_lshl_add_u64 v[208:209], s[54:55], 0, v[132:133]
	s_mov_b32 m0, s61
	s_nop 0
	global_load_lds_dwordx4 v[208:209], off
	s_waitcnt lgkmcnt(8)
	s_barrier
	s_waitcnt lgkmcnt(0)
	v_mfma_f32_16x16x32_bf16 v[124:127], v[148:151], v[172:175], v[124:127]
	v_mfma_f32_16x16x32_bf16 v[120:123], v[164:167], v[172:175], v[120:123]
	v_mfma_f32_16x16x32_bf16 v[108:111], v[148:151], v[180:183], v[108:111]
	v_mfma_f32_16x16x32_bf16 v[104:107], v[164:167], v[180:183], v[104:107]
	v_mfma_f32_16x16x32_bf16 v[92:95], v[148:151], v[188:191], v[92:95]
	v_mfma_f32_16x16x32_bf16 v[88:91], v[164:167], v[188:191], v[88:91]
	v_mfma_f32_16x16x32_bf16 v[76:79], v[148:151], v[200:203], v[76:79]
	v_mfma_f32_16x16x32_bf16 v[72:75], v[164:167], v[200:203], v[72:75]
	v_mfma_f32_16x16x32_bf16 v[124:127], v[152:155], v[176:179], v[124:127]
	v_mfma_f32_16x16x32_bf16 v[120:123], v[168:171], v[176:179], v[120:123]
	v_mfma_f32_16x16x32_bf16 v[108:111], v[152:155], v[184:187], v[108:111]
	v_mfma_f32_16x16x32_bf16 v[104:107], v[168:171], v[184:187], v[104:107]
	v_mfma_f32_16x16x32_bf16 v[92:95], v[152:155], v[196:199], v[92:95]
	v_mfma_f32_16x16x32_bf16 v[88:91], v[168:171], v[196:199], v[88:91]
	v_mfma_f32_16x16x32_bf16 v[76:79], v[152:155], v[204:207], v[76:79]
	v_mfma_f32_16x16x32_bf16 v[72:75], v[168:171], v[204:207], v[72:75]
	s_barrier
	s_add_i32 s54, 0, 0x1c000
	s_add_i32 s55, s93, s57
	v_add_u32_e32 v136, s54, v158
	v_lshl_add_u64 v[156:157], v[156:157], 0, s[0:1]
	s_mov_b32 m0, s55
	ds_read_b128 v[208:211], v136
	ds_read_b128 v[212:215], v136 offset:1024
	ds_read_b128 v[216:219], v136 offset:2048
	ds_read_b128 v[220:223], v136 offset:3072
	global_load_lds_dwordx4 v[156:157], off
	v_lshl_add_u64 v[156:157], v[224:225], 0, s[0:1]
	s_add_i32 m0, s55, 0x2000
	s_nop 0
	global_load_lds_dwordx4 v[156:157], off
	s_barrier
	s_waitcnt lgkmcnt(0)
	v_mfma_f32_16x16x32_bf16 v[116:119], v[208:211], v[172:175], v[116:119]
	v_mfma_f32_16x16x32_bf16 v[112:115], v[216:219], v[172:175], v[112:115]
	v_mfma_f32_16x16x32_bf16 v[100:103], v[208:211], v[180:183], v[100:103]
	v_mfma_f32_16x16x32_bf16 v[96:99], v[216:219], v[180:183], v[96:99]
	v_mfma_f32_16x16x32_bf16 v[84:87], v[208:211], v[188:191], v[84:87]
	v_mfma_f32_16x16x32_bf16 v[80:83], v[216:219], v[188:191], v[80:83]
	v_mfma_f32_16x16x32_bf16 v[68:71], v[208:211], v[200:203], v[68:71]
	v_mfma_f32_16x16x32_bf16 v[64:67], v[216:219], v[200:203], v[64:67]
	v_mfma_f32_16x16x32_bf16 v[116:119], v[212:215], v[176:179], v[116:119]
	v_mfma_f32_16x16x32_bf16 v[112:115], v[220:223], v[176:179], v[112:115]
	v_mfma_f32_16x16x32_bf16 v[100:103], v[212:215], v[184:187], v[100:103]
	v_mfma_f32_16x16x32_bf16 v[96:99], v[220:223], v[184:187], v[96:99]
	v_mfma_f32_16x16x32_bf16 v[84:87], v[212:215], v[196:199], v[84:87]
	v_mfma_f32_16x16x32_bf16 v[80:83], v[220:223], v[196:199], v[80:83]
	v_mfma_f32_16x16x32_bf16 v[68:71], v[212:215], v[204:207], v[68:71]
	v_mfma_f32_16x16x32_bf16 v[64:67], v[220:223], v[204:207], v[64:67]
	s_mov_b32 m0, s65
	v_lshl_add_u64 v[156:157], v[226:227], 0, s[0:1]
	s_barrier
	ds_read_b128 v[172:175], v160 offset:49152
	ds_read_b128 v[176:179], v160 offset:50176
	ds_read_b128 v[180:183], v160 offset:51200
	ds_read_b128 v[184:187], v160 offset:52224
	ds_read_b128 v[188:191], v160 offset:53248
	ds_read_b128 v[196:199], v160 offset:54272
	ds_read_b128 v[200:203], v160 offset:55296
	ds_read_b128 v[204:207], v160 offset:56320
	global_load_lds_dwordx4 v[156:157], off
	v_lshl_add_u64 v[156:157], v[228:229], 0, s[0:1]
	s_mov_b32 m0, s66
	s_nop 0
	global_load_lds_dwordx4 v[156:157], off
	s_barrier
	s_waitcnt lgkmcnt(0)
	v_mfma_f32_16x16x32_bf16 v[60:63], v[148:151], v[172:175], v[60:63]
	v_mfma_f32_16x16x32_bf16 v[56:59], v[164:167], v[172:175], v[56:59]
	v_mfma_f32_16x16x32_bf16 v[44:47], v[148:151], v[180:183], v[44:47]
	v_mfma_f32_16x16x32_bf16 v[40:43], v[164:167], v[180:183], v[40:43]
	v_mfma_f32_16x16x32_bf16 v[28:31], v[148:151], v[188:191], v[28:31]
	v_mfma_f32_16x16x32_bf16 v[24:27], v[164:167], v[188:191], v[24:27]
	v_mfma_f32_16x16x32_bf16 v[12:15], v[148:151], v[200:203], v[12:15]
	v_mfma_f32_16x16x32_bf16 v[8:11], v[164:167], v[200:203], v[8:11]
	v_mfma_f32_16x16x32_bf16 v[60:63], v[152:155], v[176:179], v[60:63]
	v_mfma_f32_16x16x32_bf16 v[56:59], v[168:171], v[176:179], v[56:59]
	v_mfma_f32_16x16x32_bf16 v[44:47], v[152:155], v[184:187], v[44:47]
	v_mfma_f32_16x16x32_bf16 v[40:43], v[168:171], v[184:187], v[40:43]
	v_mfma_f32_16x16x32_bf16 v[28:31], v[152:155], v[196:199], v[28:31]
	v_mfma_f32_16x16x32_bf16 v[24:27], v[168:171], v[196:199], v[24:27]
	v_mfma_f32_16x16x32_bf16 v[12:15], v[152:155], v[204:207], v[12:15]
	v_mfma_f32_16x16x32_bf16 v[8:11], v[168:171], v[204:207], v[8:11]
	s_barrier
	s_add_u32 s52, s52, 0x10080
	s_addc_u32 s53, s53, 0
	s_add_i32 s54, s54, s57
	v_lshl_add_u64 v[148:149], s[52:53], 0, v[130:131]
	s_mov_b32 m0, s54
	s_nop 0
	global_load_lds_dwordx4 v[148:149], off
	v_lshl_add_u64 v[148:149], s[52:53], 0, v[134:135]
	s_add_i32 m0, s54, 0x2000
	s_nop 0
	global_load_lds_dwordx4 v[148:149], off
	s_waitcnt vmcnt(6)
	s_barrier
	v_mfma_f32_16x16x32_bf16 v[52:55], v[208:211], v[172:175], v[52:55]
	v_mfma_f32_16x16x32_bf16 v[48:51], v[216:219], v[172:175], v[48:51]
	v_mfma_f32_16x16x32_bf16 v[36:39], v[208:211], v[180:183], v[36:39]
	v_mfma_f32_16x16x32_bf16 v[32:35], v[216:219], v[180:183], v[32:35]
	v_mfma_f32_16x16x32_bf16 v[20:23], v[208:211], v[188:191], v[20:23]
	v_mfma_f32_16x16x32_bf16 v[16:19], v[216:219], v[188:191], v[16:19]
	v_mfma_f32_16x16x32_bf16 v[4:7], v[208:211], v[200:203], v[4:7]
	v_mfma_f32_16x16x32_bf16 v[0:3], v[216:219], v[200:203], v[0:3]
	v_mfma_f32_16x16x32_bf16 v[52:55], v[212:215], v[176:179], v[52:55]
	v_mfma_f32_16x16x32_bf16 v[48:51], v[220:223], v[176:179], v[48:51]
	v_mfma_f32_16x16x32_bf16 v[36:39], v[212:215], v[184:187], v[36:39]
	v_mfma_f32_16x16x32_bf16 v[32:35], v[220:223], v[184:187], v[32:35]
	v_mfma_f32_16x16x32_bf16 v[20:23], v[212:215], v[196:199], v[20:23]
	v_mfma_f32_16x16x32_bf16 v[16:19], v[220:223], v[196:199], v[16:19]
	v_mfma_f32_16x16x32_bf16 v[4:7], v[212:215], v[204:207], v[4:7]
	v_mfma_f32_16x16x32_bf16 v[0:3], v[220:223], v[204:207], v[0:3]
	s_add_i32 s92, s92, 2
	s_add_u32 s50, s50, 0x100
	s_addc_u32 s51, s51, 0
	s_add_u32 s45, s45, 0x100
	s_addc_u32 s91, s91, 0
	s_cmp_gt_u32 s92, 13
	s_barrier
	s_cbranch_scc0 .LBB0_178
	v_lshl_add_u32 v148, s12, 8, v139
	v_mov_b32_e32 v149, v138
	v_add_u32_e32 v192, -8, v148
	v_cndmask_b32_e64 v192, v192, v148, s[6:7]
	s_lshl_b32 s11, s10, 8
	s_or_b32 s11, s11, s87
	s_cmp_gt_i32 s10, 11
	s_cbranch_scc1 .Le1_gates
	s_lshr_b32 s13, s10, 1
	s_lshl_b32 s50, s13, 25
	s_add_u32 s50, s20, s50
	s_addc_u32 s51, s21, 0
	s_bfe_u32 s17, s11, 0x30006
	v_ashrrev_i32_e32 v150, 8, v192
	v_and_or_b32 v150, v150, -8, s17
	v_mov_b32_e32 v151, 0
	v_lshlrev_b64 v[150:151], 18, v[150:151]
	v_lshlrev_b32_e32 v136, 7, v192
	v_and_b32_e32 v136, 0x3ff80, v136
	v_lshl_add_u32 v136, v149, 1, v136
	v_lshl_add_u64 v[150:151], v[150:151], 0, v[136:137]
	v_lshl_add_u64 v[150:151], v[150:151], 0, s[50:51]
	s_movk_i32 s11, 0x800
	s_movk_i32 s17, 0x2800
	s_movk_i32 s54, 0x400
	s_branch .Le1_addr
.Le1_gates:
	v_or_b32_e32 v136, s11, v149
	v_lshlrev_b32_e32 v136, 1, v136
	v_mov_b32_e32 v150, v192
	v_mov_b32_e32 v151, 0
	v_lshlrev_b64 v[150:151], 12, v[150:151]
	v_lshl_add_u64 v[150:151], v[150:151], 0, v[136:137]
	s_add_u32 s50, s38, s40
	s_addc_u32 s51, s39, s41
	v_lshl_add_u64 v[150:151], v[150:151], 0, s[50:51]
	s_mov_b32 s11, 0x10000
	s_mov_b32 s17, 0x50000
	s_mov_b32 s54, 0x8000
.Le1_addr:
	s_mov_b32 s55, 0
	v_lshl_add_u64 v[182:183], v[150:151], 0, s[54:55]
	s_mov_b64 s[50:51], 0
	s_cmp_lt_i32 s10, 4
	s_cbranch_scc1 .Le1_rope
	v_cvt_pk_bf16_f32 v124, v124, v125
	v_cvt_pk_bf16_f32 v125, v126, v127
	v_cvt_pk_bf16_f32 v126, v120, v121
	v_cvt_pk_bf16_f32 v127, v122, v123
	v_cvt_pk_bf16_f32 v116, v116, v117
	v_cvt_pk_bf16_f32 v117, v118, v119
	v_cvt_pk_bf16_f32 v118, v112, v113
	v_cvt_pk_bf16_f32 v119, v114, v115
	v_cndmask_b32_e64 v174, v124, v116, s[6:7]
	v_cndmask_b32_e64 v175, v125, v117, s[6:7]
	v_cndmask_b32_e64 v176, v126, v118, s[6:7]
	v_cndmask_b32_e64 v177, v127, v119, s[6:7]
	v_mov_b32_dpp v178, v174 row_ror:8 row_mask:0xf bank_mask:0xf
	v_mov_b32_dpp v179, v175 row_ror:8 row_mask:0xf bank_mask:0xf
	v_mov_b32_dpp v180, v176 row_ror:8 row_mask:0xf bank_mask:0xf
	v_mov_b32_dpp v181, v177 row_ror:8 row_mask:0xf bank_mask:0xf
	v_cndmask_b32_e64 v116, v116, v178, s[6:7]
	v_cndmask_b32_e64 v124, v178, v124, s[6:7]
	v_cndmask_b32_e64 v117, v117, v179, s[6:7]
	v_cndmask_b32_e64 v125, v179, v125, s[6:7]
	v_cndmask_b32_e64 v118, v118, v180, s[6:7]
	v_cndmask_b32_e64 v126, v180, v126, s[6:7]
	v_cndmask_b32_e64 v119, v119, v181, s[6:7]
	v_cndmask_b32_e64 v127, v181, v127, s[6:7]
	v_lshl_add_u64 v[152:153], v[150:151], 0, s[50:51]
	v_lshl_add_u64 v[184:185], v[182:183], 0, s[50:51]
	global_store_dwordx4 v[152:153], v[124:127], off
	global_store_dwordx4 v[184:185], v[116:119], off
	s_add_u32 s50, s50, s11
	s_addc_u32 s51, s51, 0
	v_cvt_pk_bf16_f32 v108, v108, v109
	v_cvt_pk_bf16_f32 v109, v110, v111
	v_cvt_pk_bf16_f32 v110, v104, v105
	v_cvt_pk_bf16_f32 v111, v106, v107
	v_cvt_pk_bf16_f32 v100, v100, v101
	v_cvt_pk_bf16_f32 v101, v102, v103
	v_cvt_pk_bf16_f32 v102, v96, v97
	v_cvt_pk_bf16_f32 v103, v98, v99
	v_cndmask_b32_e64 v174, v108, v100, s[6:7]
	v_cndmask_b32_e64 v175, v109, v101, s[6:7]
	v_cndmask_b32_e64 v176, v110, v102, s[6:7]
	v_cndmask_b32_e64 v177, v111, v103, s[6:7]
	v_mov_b32_dpp v178, v174 row_ror:8 row_mask:0xf bank_mask:0xf
	v_mov_b32_dpp v179, v175 row_ror:8 row_mask:0xf bank_mask:0xf
	v_mov_b32_dpp v180, v176 row_ror:8 row_mask:0xf bank_mask:0xf
	v_mov_b32_dpp v181, v177 row_ror:8 row_mask:0xf bank_mask:0xf
	v_cndmask_b32_e64 v100, v100, v178, s[6:7]
	v_cndmask_b32_e64 v108, v178, v108, s[6:7]
	v_cndmask_b32_e64 v101, v101, v179, s[6:7]
	v_cndmask_b32_e64 v109, v179, v109, s[6:7]
	v_cndmask_b32_e64 v102, v102, v180, s[6:7]
	v_cndmask_b32_e64 v110, v180, v110, s[6:7]
	v_cndmask_b32_e64 v103, v103, v181, s[6:7]
	v_cndmask_b32_e64 v111, v181, v111, s[6:7]
	v_lshl_add_u64 v[154:155], v[150:151], 0, s[50:51]
	v_lshl_add_u64 v[240:241], v[182:183], 0, s[50:51]
	global_store_dwordx4 v[154:155], v[108:111], off
	global_store_dwordx4 v[240:241], v[100:103], off
	s_add_u32 s50, s50, s11
	s_addc_u32 s51, s51, 0
	v_cvt_pk_bf16_f32 v92, v92, v93
	v_cvt_pk_bf16_f32 v93, v94, v95
	v_cvt_pk_bf16_f32 v94, v88, v89
	v_cvt_pk_bf16_f32 v95, v90, v91
	v_cvt_pk_bf16_f32 v84, v84, v85
	v_cvt_pk_bf16_f32 v85, v86, v87
	v_cvt_pk_bf16_f32 v86, v80, v81
	v_cvt_pk_bf16_f32 v87, v82, v83
	v_cndmask_b32_e64 v174, v92, v84, s[6:7]
	v_cndmask_b32_e64 v175, v93, v85, s[6:7]
	v_cndmask_b32_e64 v176, v94, v86, s[6:7]
	v_cndmask_b32_e64 v177, v95, v87, s[6:7]
	v_mov_b32_dpp v178, v174 row_ror:8 row_mask:0xf bank_mask:0xf
	v_mov_b32_dpp v179, v175 row_ror:8 row_mask:0xf bank_mask:0xf
	v_mov_b32_dpp v180, v176 row_ror:8 row_mask:0xf bank_mask:0xf
	v_mov_b32_dpp v181, v177 row_ror:8 row_mask:0xf bank_mask:0xf
	v_cndmask_b32_e64 v84, v84, v178, s[6:7]
	v_cndmask_b32_e64 v92, v178, v92, s[6:7]
	v_cndmask_b32_e64 v85, v85, v179, s[6:7]
	v_cndmask_b32_e64 v93, v179, v93, s[6:7]
	v_cndmask_b32_e64 v86, v86, v180, s[6:7]
	v_cndmask_b32_e64 v94, v180, v94, s[6:7]
	v_cndmask_b32_e64 v87, v87, v181, s[6:7]
	v_cndmask_b32_e64 v95, v181, v95, s[6:7]
	v_lshl_add_u64 v[152:153], v[150:151], 0, s[50:51]
	v_lshl_add_u64 v[184:185], v[182:183], 0, s[50:51]
	global_store_dwordx4 v[152:153], v[92:95], off
	global_store_dwordx4 v[184:185], v[84:87], off
	s_add_u32 s50, s50, s11
	s_addc_u32 s51, s51, 0
	v_cvt_pk_bf16_f32 v76, v76, v77
	v_cvt_pk_bf16_f32 v77, v78, v79
	v_cvt_pk_bf16_f32 v78, v72, v73
	v_cvt_pk_bf16_f32 v79, v74, v75
	v_cvt_pk_bf16_f32 v68, v68, v69
	v_cvt_pk_bf16_f32 v69, v70, v71
	v_cvt_pk_bf16_f32 v70, v64, v65
	v_cvt_pk_bf16_f32 v71, v66, v67
	v_cndmask_b32_e64 v174, v76, v68, s[6:7]
	v_cndmask_b32_e64 v175, v77, v69, s[6:7]
	v_cndmask_b32_e64 v176, v78, v70, s[6:7]
	v_cndmask_b32_e64 v177, v79, v71, s[6:7]
	v_mov_b32_dpp v178, v174 row_ror:8 row_mask:0xf bank_mask:0xf
	v_mov_b32_dpp v179, v175 row_ror:8 row_mask:0xf bank_mask:0xf
	v_mov_b32_dpp v180, v176 row_ror:8 row_mask:0xf bank_mask:0xf
	v_mov_b32_dpp v181, v177 row_ror:8 row_mask:0xf bank_mask:0xf
	v_cndmask_b32_e64 v68, v68, v178, s[6:7]
	v_cndmask_b32_e64 v76, v178, v76, s[6:7]
	v_cndmask_b32_e64 v69, v69, v179, s[6:7]
	v_cndmask_b32_e64 v77, v179, v77, s[6:7]
	v_cndmask_b32_e64 v70, v70, v180, s[6:7]
	v_cndmask_b32_e64 v78, v180, v78, s[6:7]
	v_cndmask_b32_e64 v71, v71, v181, s[6:7]
	v_cndmask_b32_e64 v79, v181, v79, s[6:7]
	v_lshl_add_u64 v[154:155], v[150:151], 0, s[50:51]
	v_lshl_add_u64 v[240:241], v[182:183], 0, s[50:51]
	global_store_dwordx4 v[154:155], v[76:79], off
	global_store_dwordx4 v[240:241], v[68:71], off
	s_add_u32 s50, s50, s17
	s_addc_u32 s51, s51, 0
	v_cvt_pk_bf16_f32 v60, v60, v61
	v_cvt_pk_bf16_f32 v61, v62, v63
	v_cvt_pk_bf16_f32 v62, v56, v57
	v_cvt_pk_bf16_f32 v63, v58, v59
	v_cvt_pk_bf16_f32 v52, v52, v53
	v_cvt_pk_bf16_f32 v53, v54, v55
	v_cvt_pk_bf16_f32 v54, v48, v49
	v_cvt_pk_bf16_f32 v55, v50, v51
	v_cndmask_b32_e64 v174, v60, v52, s[6:7]
	v_cndmask_b32_e64 v175, v61, v53, s[6:7]
	v_cndmask_b32_e64 v176, v62, v54, s[6:7]
	v_cndmask_b32_e64 v177, v63, v55, s[6:7]
	v_mov_b32_dpp v178, v174 row_ror:8 row_mask:0xf bank_mask:0xf
	v_mov_b32_dpp v179, v175 row_ror:8 row_mask:0xf bank_mask:0xf
	v_mov_b32_dpp v180, v176 row_ror:8 row_mask:0xf bank_mask:0xf
	v_mov_b32_dpp v181, v177 row_ror:8 row_mask:0xf bank_mask:0xf
	v_cndmask_b32_e64 v52, v52, v178, s[6:7]
	v_cndmask_b32_e64 v60, v178, v60, s[6:7]
	v_cndmask_b32_e64 v53, v53, v179, s[6:7]
	v_cndmask_b32_e64 v61, v179, v61, s[6:7]
	v_cndmask_b32_e64 v54, v54, v180, s[6:7]
	v_cndmask_b32_e64 v62, v180, v62, s[6:7]
	v_cndmask_b32_e64 v55, v55, v181, s[6:7]
	v_cndmask_b32_e64 v63, v181, v63, s[6:7]
	v_lshl_add_u64 v[152:153], v[150:151], 0, s[50:51]
	v_lshl_add_u64 v[184:185], v[182:183], 0, s[50:51]
	global_store_dwordx4 v[152:153], v[60:63], off
	global_store_dwordx4 v[184:185], v[52:55], off
	s_add_u32 s50, s50, s11
	s_addc_u32 s51, s51, 0
	v_cvt_pk_bf16_f32 v44, v44, v45
	v_cvt_pk_bf16_f32 v45, v46, v47
	v_cvt_pk_bf16_f32 v46, v40, v41
	v_cvt_pk_bf16_f32 v47, v42, v43
	v_cvt_pk_bf16_f32 v36, v36, v37
	v_cvt_pk_bf16_f32 v37, v38, v39
	v_cvt_pk_bf16_f32 v38, v32, v33
	v_cvt_pk_bf16_f32 v39, v34, v35
	v_cndmask_b32_e64 v174, v44, v36, s[6:7]
	v_cndmask_b32_e64 v175, v45, v37, s[6:7]
	v_cndmask_b32_e64 v176, v46, v38, s[6:7]
	v_cndmask_b32_e64 v177, v47, v39, s[6:7]
	v_mov_b32_dpp v178, v174 row_ror:8 row_mask:0xf bank_mask:0xf
	v_mov_b32_dpp v179, v175 row_ror:8 row_mask:0xf bank_mask:0xf
	v_mov_b32_dpp v180, v176 row_ror:8 row_mask:0xf bank_mask:0xf
	v_mov_b32_dpp v181, v177 row_ror:8 row_mask:0xf bank_mask:0xf
	v_cndmask_b32_e64 v36, v36, v178, s[6:7]
	v_cndmask_b32_e64 v44, v178, v44, s[6:7]
	v_cndmask_b32_e64 v37, v37, v179, s[6:7]
	v_cndmask_b32_e64 v45, v179, v45, s[6:7]
	v_cndmask_b32_e64 v38, v38, v180, s[6:7]
	v_cndmask_b32_e64 v46, v180, v46, s[6:7]
	v_cndmask_b32_e64 v39, v39, v181, s[6:7]
	v_cndmask_b32_e64 v47, v181, v47, s[6:7]
	v_lshl_add_u64 v[154:155], v[150:151], 0, s[50:51]
	v_lshl_add_u64 v[240:241], v[182:183], 0, s[50:51]
	global_store_dwordx4 v[154:155], v[44:47], off
	global_store_dwordx4 v[240:241], v[36:39], off
	s_add_u32 s50, s50, s11
	s_addc_u32 s51, s51, 0
	v_cvt_pk_bf16_f32 v28, v28, v29
	v_cvt_pk_bf16_f32 v29, v30, v31
	v_cvt_pk_bf16_f32 v30, v24, v25
	v_cvt_pk_bf16_f32 v31, v26, v27
	v_cvt_pk_bf16_f32 v20, v20, v21
	v_cvt_pk_bf16_f32 v21, v22, v23
	v_cvt_pk_bf16_f32 v22, v16, v17
	v_cvt_pk_bf16_f32 v23, v18, v19
	v_cndmask_b32_e64 v174, v28, v20, s[6:7]
	v_cndmask_b32_e64 v175, v29, v21, s[6:7]
	v_cndmask_b32_e64 v176, v30, v22, s[6:7]
	v_cndmask_b32_e64 v177, v31, v23, s[6:7]
	v_mov_b32_dpp v178, v174 row_ror:8 row_mask:0xf bank_mask:0xf
	v_mov_b32_dpp v179, v175 row_ror:8 row_mask:0xf bank_mask:0xf
	v_mov_b32_dpp v180, v176 row_ror:8 row_mask:0xf bank_mask:0xf
	v_mov_b32_dpp v181, v177 row_ror:8 row_mask:0xf bank_mask:0xf
	v_cndmask_b32_e64 v20, v20, v178, s[6:7]
	v_cndmask_b32_e64 v28, v178, v28, s[6:7]
	v_cndmask_b32_e64 v21, v21, v179, s[6:7]
	v_cndmask_b32_e64 v29, v179, v29, s[6:7]
	v_cndmask_b32_e64 v22, v22, v180, s[6:7]
	v_cndmask_b32_e64 v30, v180, v30, s[6:7]
	v_cndmask_b32_e64 v23, v23, v181, s[6:7]
	v_cndmask_b32_e64 v31, v181, v31, s[6:7]
	v_lshl_add_u64 v[152:153], v[150:151], 0, s[50:51]
	v_lshl_add_u64 v[184:185], v[182:183], 0, s[50:51]
	global_store_dwordx4 v[152:153], v[28:31], off
	global_store_dwordx4 v[184:185], v[20:23], off
	s_add_u32 s50, s50, s11
	s_addc_u32 s51, s51, 0
	v_cvt_pk_bf16_f32 v12, v12, v13
	v_cvt_pk_bf16_f32 v13, v14, v15
	v_cvt_pk_bf16_f32 v14, v8, v9
	v_cvt_pk_bf16_f32 v15, v10, v11
	v_cvt_pk_bf16_f32 v4, v4, v5
	v_cvt_pk_bf16_f32 v5, v6, v7
	v_cvt_pk_bf16_f32 v6, v0, v1
	v_cvt_pk_bf16_f32 v7, v2, v3
	v_cndmask_b32_e64 v174, v12, v4, s[6:7]
	v_cndmask_b32_e64 v175, v13, v5, s[6:7]
	v_cndmask_b32_e64 v176, v14, v6, s[6:7]
	v_cndmask_b32_e64 v177, v15, v7, s[6:7]
	v_mov_b32_dpp v178, v174 row_ror:8 row_mask:0xf bank_mask:0xf
	v_mov_b32_dpp v179, v175 row_ror:8 row_mask:0xf bank_mask:0xf
	v_mov_b32_dpp v180, v176 row_ror:8 row_mask:0xf bank_mask:0xf
	v_mov_b32_dpp v181, v177 row_ror:8 row_mask:0xf bank_mask:0xf
	v_cndmask_b32_e64 v4, v4, v178, s[6:7]
	v_cndmask_b32_e64 v12, v178, v12, s[6:7]
	v_cndmask_b32_e64 v5, v5, v179, s[6:7]
	v_cndmask_b32_e64 v13, v179, v13, s[6:7]
	v_cndmask_b32_e64 v6, v6, v180, s[6:7]
	v_cndmask_b32_e64 v14, v180, v14, s[6:7]
	v_cndmask_b32_e64 v7, v7, v181, s[6:7]
	v_cndmask_b32_e64 v15, v181, v15, s[6:7]
	v_lshl_add_u64 v[154:155], v[150:151], 0, s[50:51]
	v_lshl_add_u64 v[240:241], v[182:183], 0, s[50:51]
	global_store_dwordx4 v[154:155], v[12:15], off
	global_store_dwordx4 v[240:241], v[4:7], off
	s_branch .LBB0_174
.Le1_rope:
	v_xor_b32_e32 v156, 16, v162
	v_lshlrev_b32_e32 v156, 2, v156
	v_mov_b32_e32 v164, 1.0
	v_cndmask_b32_e64 v164, v164, -1.0, s[4:5]
	v_lshlrev_b32_e32 v190, 6, v148
	s_and_saveexec_b64 s[12:13], s[2:3]
	global_load_dwordx4 v[196:199], v190, s[84:85] offset:32
	global_load_dwordx4 v[200:203], v190, s[84:85] offset:48
	global_load_dwordx4 v[204:207], v190, s[84:85]
	global_load_dwordx4 v[208:211], v190, s[84:85] offset:16
	v_add_u32_e32 v191, 0x400, v190
	global_load_dwordx4 v[212:215], v191, s[84:85] offset:32
	global_load_dwordx4 v[216:219], v191, s[84:85] offset:48
	global_load_dwordx4 v[220:223], v191, s[84:85]
	global_load_dwordx4 v[224:227], v191, s[84:85] offset:16
	v_add_u32_e32 v191, 0x800, v190
	global_load_dwordx4 v[228:231], v191, s[84:85] offset:32
	global_load_dwordx4 v[232:235], v191, s[84:85] offset:48
	global_load_dwordx4 v[236:239], v191, s[84:85]
	global_load_dwordx4 v[186:189], v191, s[84:85] offset:16
	s_or_b64 exec, exec, s[12:13]
	ds_bpermute_b32 v166, v156, v124
	ds_bpermute_b32 v167, v156, v125
	ds_bpermute_b32 v168, v156, v126
	ds_bpermute_b32 v169, v156, v127
	ds_bpermute_b32 v170, v156, v120
	ds_bpermute_b32 v171, v156, v121
	ds_bpermute_b32 v172, v156, v122
	ds_bpermute_b32 v173, v156, v123
	s_and_saveexec_b64 s[12:13], s[2:3]
	s_waitcnt vmcnt(8)
	v_pk_mul_f32 v[196:197], v[196:197], v[164:165] op_sel_hi:[1,0]
	v_pk_mul_f32 v[200:201], v[200:201], v[164:165] op_sel_hi:[1,0]
	v_pk_mul_f32 v[198:199], v[198:199], v[164:165] op_sel_hi:[1,0]
	v_pk_mul_f32 v[202:203], v[202:203], v[164:165] op_sel_hi:[1,0]
	s_waitcnt lgkmcnt(0)
	v_pk_mul_f32 v[166:167], v[196:197], v[166:167]
	v_pk_mul_f32 v[170:171], v[200:201], v[170:171]
	v_pk_mul_f32 v[168:169], v[198:199], v[168:169]
	v_pk_mul_f32 v[172:173], v[202:203], v[172:173]
	v_pk_fma_f32 v[124:125], v[124:125], v[204:205], v[166:167]
	v_pk_fma_f32 v[120:121], v[120:121], v[208:209], v[170:171]
	v_pk_fma_f32 v[126:127], v[126:127], v[206:207], v[168:169]
	v_pk_fma_f32 v[122:123], v[122:123], v[210:211], v[172:173]
	v_add_u32_e32 v191, 0xc00, v190
	global_load_dwordx4 v[196:199], v191, s[84:85] offset:32
	global_load_dwordx4 v[200:203], v191, s[84:85] offset:48
	global_load_dwordx4 v[204:207], v191, s[84:85]
	global_load_dwordx4 v[208:211], v191, s[84:85] offset:16
	s_or_b64 exec, exec, s[12:13]
	v_cvt_pk_bf16_f32 v124, v124, v125
	v_cvt_pk_bf16_f32 v125, v126, v127
	v_cvt_pk_bf16_f32 v126, v120, v121
	v_cvt_pk_bf16_f32 v127, v122, v123
	v_cvt_pk_bf16_f32 v116, v116, v117
	v_cvt_pk_bf16_f32 v117, v118, v119
	v_cvt_pk_bf16_f32 v118, v112, v113
	v_cvt_pk_bf16_f32 v119, v114, v115
	v_cndmask_b32_e64 v174, v124, v116, s[6:7]
	v_cndmask_b32_e64 v175, v125, v117, s[6:7]
	v_cndmask_b32_e64 v176, v126, v118, s[6:7]
	v_cndmask_b32_e64 v177, v127, v119, s[6:7]
	v_mov_b32_dpp v178, v174 row_ror:8 row_mask:0xf bank_mask:0xf
	v_mov_b32_dpp v179, v175 row_ror:8 row_mask:0xf bank_mask:0xf
	v_mov_b32_dpp v180, v176 row_ror:8 row_mask:0xf bank_mask:0xf
	v_mov_b32_dpp v181, v177 row_ror:8 row_mask:0xf bank_mask:0xf
	v_cndmask_b32_e64 v116, v116, v178, s[6:7]
	v_cndmask_b32_e64 v124, v178, v124, s[6:7]
	v_cndmask_b32_e64 v117, v117, v179, s[6:7]
	v_cndmask_b32_e64 v125, v179, v125, s[6:7]
	v_cndmask_b32_e64 v118, v118, v180, s[6:7]
	v_cndmask_b32_e64 v126, v180, v126, s[6:7]
	v_cndmask_b32_e64 v119, v119, v181, s[6:7]
	v_cndmask_b32_e64 v127, v181, v127, s[6:7]
	v_lshl_add_u64 v[152:153], v[150:151], 0, s[50:51]
	v_lshl_add_u64 v[184:185], v[182:183], 0, s[50:51]
	global_store_dwordx4 v[152:153], v[124:127], off
	global_store_dwordx4 v[184:185], v[116:119], off
	s_add_u32 s50, s50, s11
	s_addc_u32 s51, s51, 0
	ds_bpermute_b32 v166, v156, v108
	ds_bpermute_b32 v167, v156, v109
	ds_bpermute_b32 v168, v156, v110
	ds_bpermute_b32 v169, v156, v111
	ds_bpermute_b32 v170, v156, v104
	ds_bpermute_b32 v171, v156, v105
	ds_bpermute_b32 v172, v156, v106
	ds_bpermute_b32 v173, v156, v107
	s_and_saveexec_b64 s[12:13], s[2:3]
	s_waitcnt vmcnt(10)
	v_pk_mul_f32 v[212:213], v[212:213], v[164:165] op_sel_hi:[1,0]
	v_pk_mul_f32 v[216:217], v[216:217], v[164:165] op_sel_hi:[1,0]
	v_pk_mul_f32 v[214:215], v[214:215], v[164:165] op_sel_hi:[1,0]
	v_pk_mul_f32 v[218:219], v[218:219], v[164:165] op_sel_hi:[1,0]
	s_waitcnt lgkmcnt(0)
	v_pk_mul_f32 v[166:167], v[212:213], v[166:167]
	v_pk_mul_f32 v[170:171], v[216:217], v[170:171]
	v_pk_mul_f32 v[168:169], v[214:215], v[168:169]
	v_pk_mul_f32 v[172:173], v[218:219], v[172:173]
	v_pk_fma_f32 v[108:109], v[108:109], v[220:221], v[166:167]
	v_pk_fma_f32 v[104:105], v[104:105], v[224:225], v[170:171]
	v_pk_fma_f32 v[110:111], v[110:111], v[222:223], v[168:169]
	v_pk_fma_f32 v[106:107], v[106:107], v[226:227], v[172:173]
	v_add_u32_e32 v191, 0x2000, v190
	global_load_dwordx4 v[212:215], v191, s[84:85] offset:32
	global_load_dwordx4 v[216:219], v191, s[84:85] offset:48
	global_load_dwordx4 v[220:223], v191, s[84:85]
	global_load_dwordx4 v[224:227], v191, s[84:85] offset:16
	s_or_b64 exec, exec, s[12:13]
	v_cvt_pk_bf16_f32 v108, v108, v109
	v_cvt_pk_bf16_f32 v109, v110, v111
	v_cvt_pk_bf16_f32 v110, v104, v105
	v_cvt_pk_bf16_f32 v111, v106, v107
	v_cvt_pk_bf16_f32 v100, v100, v101
	v_cvt_pk_bf16_f32 v101, v102, v103
	v_cvt_pk_bf16_f32 v102, v96, v97
	v_cvt_pk_bf16_f32 v103, v98, v99
	v_cndmask_b32_e64 v174, v108, v100, s[6:7]
	v_cndmask_b32_e64 v175, v109, v101, s[6:7]
	v_cndmask_b32_e64 v176, v110, v102, s[6:7]
	v_cndmask_b32_e64 v177, v111, v103, s[6:7]
	v_mov_b32_dpp v178, v174 row_ror:8 row_mask:0xf bank_mask:0xf
	v_mov_b32_dpp v179, v175 row_ror:8 row_mask:0xf bank_mask:0xf
	v_mov_b32_dpp v180, v176 row_ror:8 row_mask:0xf bank_mask:0xf
	v_mov_b32_dpp v181, v177 row_ror:8 row_mask:0xf bank_mask:0xf
	v_cndmask_b32_e64 v100, v100, v178, s[6:7]
	v_cndmask_b32_e64 v108, v178, v108, s[6:7]
	v_cndmask_b32_e64 v101, v101, v179, s[6:7]
	v_cndmask_b32_e64 v109, v179, v109, s[6:7]
	v_cndmask_b32_e64 v102, v102, v180, s[6:7]
	v_cndmask_b32_e64 v110, v180, v110, s[6:7]
	v_cndmask_b32_e64 v103, v103, v181, s[6:7]
	v_cndmask_b32_e64 v111, v181, v111, s[6:7]
	v_lshl_add_u64 v[154:155], v[150:151], 0, s[50:51]
	v_lshl_add_u64 v[240:241], v[182:183], 0, s[50:51]
	global_store_dwordx4 v[154:155], v[108:111], off
	global_store_dwordx4 v[240:241], v[100:103], off
	s_add_u32 s50, s50, s11
	s_addc_u32 s51, s51, 0
	ds_bpermute_b32 v166, v156, v92
	ds_bpermute_b32 v167, v156, v93
	ds_bpermute_b32 v168, v156, v94
	ds_bpermute_b32 v169, v156, v95
	ds_bpermute_b32 v170, v156, v88
	ds_bpermute_b32 v171, v156, v89
	ds_bpermute_b32 v172, v156, v90
	ds_bpermute_b32 v173, v156, v91
	s_and_saveexec_b64 s[12:13], s[2:3]
	s_waitcnt vmcnt(12)
	v_pk_mul_f32 v[228:229], v[228:229], v[164:165] op_sel_hi:[1,0]
	v_pk_mul_f32 v[232:233], v[232:233], v[164:165] op_sel_hi:[1,0]
	v_pk_mul_f32 v[230:231], v[230:231], v[164:165] op_sel_hi:[1,0]
	v_pk_mul_f32 v[234:235], v[234:235], v[164:165] op_sel_hi:[1,0]
	s_waitcnt lgkmcnt(0)
	v_pk_mul_f32 v[166:167], v[228:229], v[166:167]
	v_pk_mul_f32 v[170:171], v[232:233], v[170:171]
	v_pk_mul_f32 v[168:169], v[230:231], v[168:169]
	v_pk_mul_f32 v[172:173], v[234:235], v[172:173]
	v_pk_fma_f32 v[92:93], v[92:93], v[236:237], v[166:167]
	v_pk_fma_f32 v[88:89], v[88:89], v[186:187], v[170:171]
	v_pk_fma_f32 v[94:95], v[94:95], v[238:239], v[168:169]
	v_pk_fma_f32 v[90:91], v[90:91], v[188:189], v[172:173]
	v_add_u32_e32 v191, 0x2400, v190
	global_load_dwordx4 v[228:231], v191, s[84:85] offset:32
	global_load_dwordx4 v[232:235], v191, s[84:85] offset:48
	global_load_dwordx4 v[236:239], v191, s[84:85]
	global_load_dwordx4 v[186:189], v191, s[84:85] offset:16
	s_or_b64 exec, exec, s[12:13]
	v_cvt_pk_bf16_f32 v92, v92, v93
	v_cvt_pk_bf16_f32 v93, v94, v95
	v_cvt_pk_bf16_f32 v94, v88, v89
	v_cvt_pk_bf16_f32 v95, v90, v91
	v_cvt_pk_bf16_f32 v84, v84, v85
	v_cvt_pk_bf16_f32 v85, v86, v87
	v_cvt_pk_bf16_f32 v86, v80, v81
	v_cvt_pk_bf16_f32 v87, v82, v83
	v_cndmask_b32_e64 v174, v92, v84, s[6:7]
	v_cndmask_b32_e64 v175, v93, v85, s[6:7]
	v_cndmask_b32_e64 v176, v94, v86, s[6:7]
	v_cndmask_b32_e64 v177, v95, v87, s[6:7]
	v_mov_b32_dpp v178, v174 row_ror:8 row_mask:0xf bank_mask:0xf
	v_mov_b32_dpp v179, v175 row_ror:8 row_mask:0xf bank_mask:0xf
	v_mov_b32_dpp v180, v176 row_ror:8 row_mask:0xf bank_mask:0xf
	v_mov_b32_dpp v181, v177 row_ror:8 row_mask:0xf bank_mask:0xf
	v_cndmask_b32_e64 v84, v84, v178, s[6:7]
	v_cndmask_b32_e64 v92, v178, v92, s[6:7]
	v_cndmask_b32_e64 v85, v85, v179, s[6:7]
	v_cndmask_b32_e64 v93, v179, v93, s[6:7]
	v_cndmask_b32_e64 v86, v86, v180, s[6:7]
	v_cndmask_b32_e64 v94, v180, v94, s[6:7]
	v_cndmask_b32_e64 v87, v87, v181, s[6:7]
	v_cndmask_b32_e64 v95, v181, v95, s[6:7]
	v_lshl_add_u64 v[152:153], v[150:151], 0, s[50:51]
	v_lshl_add_u64 v[184:185], v[182:183], 0, s[50:51]
	global_store_dwordx4 v[152:153], v[92:95], off
	global_store_dwordx4 v[184:185], v[84:87], off
	s_add_u32 s50, s50, s11
	s_addc_u32 s51, s51, 0
	ds_bpermute_b32 v166, v156, v76
	ds_bpermute_b32 v167, v156, v77
	ds_bpermute_b32 v168, v156, v78
	ds_bpermute_b32 v169, v156, v79
	ds_bpermute_b32 v170, v156, v72
	ds_bpermute_b32 v171, v156, v73
	ds_bpermute_b32 v172, v156, v74
	ds_bpermute_b32 v173, v156, v75
	s_and_saveexec_b64 s[12:13], s[2:3]
	s_waitcnt vmcnt(14)
	v_pk_mul_f32 v[196:197], v[196:197], v[164:165] op_sel_hi:[1,0]
	v_pk_mul_f32 v[200:201], v[200:201], v[164:165] op_sel_hi:[1,0]
	v_pk_mul_f32 v[198:199], v[198:199], v[164:165] op_sel_hi:[1,0]
	v_pk_mul_f32 v[202:203], v[202:203], v[164:165] op_sel_hi:[1,0]
	s_waitcnt lgkmcnt(0)
	v_pk_mul_f32 v[166:167], v[196:197], v[166:167]
	v_pk_mul_f32 v[170:171], v[200:201], v[170:171]
	v_pk_mul_f32 v[168:169], v[198:199], v[168:169]
	v_pk_mul_f32 v[172:173], v[202:203], v[172:173]
	v_pk_fma_f32 v[76:77], v[76:77], v[204:205], v[166:167]
	v_pk_fma_f32 v[72:73], v[72:73], v[208:209], v[170:171]
	v_pk_fma_f32 v[78:79], v[78:79], v[206:207], v[168:169]
	v_pk_fma_f32 v[74:75], v[74:75], v[210:211], v[172:173]
	v_add_u32_e32 v191, 0x2800, v190
	global_load_dwordx4 v[196:199], v191, s[84:85] offset:32
	global_load_dwordx4 v[200:203], v191, s[84:85] offset:48
	global_load_dwordx4 v[204:207], v191, s[84:85]
	global_load_dwordx4 v[208:211], v191, s[84:85] offset:16
	s_or_b64 exec, exec, s[12:13]
	v_cvt_pk_bf16_f32 v76, v76, v77
	v_cvt_pk_bf16_f32 v77, v78, v79
	v_cvt_pk_bf16_f32 v78, v72, v73
	v_cvt_pk_bf16_f32 v79, v74, v75
	v_cvt_pk_bf16_f32 v68, v68, v69
	v_cvt_pk_bf16_f32 v69, v70, v71
	v_cvt_pk_bf16_f32 v70, v64, v65
	v_cvt_pk_bf16_f32 v71, v66, v67
	v_cndmask_b32_e64 v174, v76, v68, s[6:7]
	v_cndmask_b32_e64 v175, v77, v69, s[6:7]
	v_cndmask_b32_e64 v176, v78, v70, s[6:7]
	v_cndmask_b32_e64 v177, v79, v71, s[6:7]
	v_mov_b32_dpp v178, v174 row_ror:8 row_mask:0xf bank_mask:0xf
	v_mov_b32_dpp v179, v175 row_ror:8 row_mask:0xf bank_mask:0xf
	v_mov_b32_dpp v180, v176 row_ror:8 row_mask:0xf bank_mask:0xf
	v_mov_b32_dpp v181, v177 row_ror:8 row_mask:0xf bank_mask:0xf
	v_cndmask_b32_e64 v68, v68, v178, s[6:7]
	v_cndmask_b32_e64 v76, v178, v76, s[6:7]
	v_cndmask_b32_e64 v69, v69, v179, s[6:7]
	v_cndmask_b32_e64 v77, v179, v77, s[6:7]
	v_cndmask_b32_e64 v70, v70, v180, s[6:7]
	v_cndmask_b32_e64 v78, v180, v78, s[6:7]
	v_cndmask_b32_e64 v71, v71, v181, s[6:7]
	v_cndmask_b32_e64 v79, v181, v79, s[6:7]
	v_lshl_add_u64 v[154:155], v[150:151], 0, s[50:51]
	v_lshl_add_u64 v[240:241], v[182:183], 0, s[50:51]
	global_store_dwordx4 v[154:155], v[76:79], off
	global_store_dwordx4 v[240:241], v[68:71], off
	s_add_u32 s50, s50, s17
	s_addc_u32 s51, s51, 0
	ds_bpermute_b32 v166, v156, v60
	ds_bpermute_b32 v167, v156, v61
	ds_bpermute_b32 v168, v156, v62
	ds_bpermute_b32 v169, v156, v63
	ds_bpermute_b32 v170, v156, v56
	ds_bpermute_b32 v171, v156, v57
	ds_bpermute_b32 v172, v156, v58
	ds_bpermute_b32 v173, v156, v59
	s_and_saveexec_b64 s[12:13], s[2:3]
	s_waitcnt vmcnt(14)
	v_pk_mul_f32 v[212:213], v[212:213], v[164:165] op_sel_hi:[1,0]
	v_pk_mul_f32 v[216:217], v[216:217], v[164:165] op_sel_hi:[1,0]
	v_pk_mul_f32 v[214:215], v[214:215], v[164:165] op_sel_hi:[1,0]
	v_pk_mul_f32 v[218:219], v[218:219], v[164:165] op_sel_hi:[1,0]
	s_waitcnt lgkmcnt(0)
	v_pk_mul_f32 v[166:167], v[212:213], v[166:167]
	v_pk_mul_f32 v[170:171], v[216:217], v[170:171]
	v_pk_mul_f32 v[168:169], v[214:215], v[168:169]
	v_pk_mul_f32 v[172:173], v[218:219], v[172:173]
	v_pk_fma_f32 v[60:61], v[60:61], v[220:221], v[166:167]
	v_pk_fma_f32 v[56:57], v[56:57], v[224:225], v[170:171]
	v_pk_fma_f32 v[62:63], v[62:63], v[222:223], v[168:169]
	v_pk_fma_f32 v[58:59], v[58:59], v[226:227], v[172:173]
	v_add_u32_e32 v191, 0x2c00, v190
	global_load_dwordx4 v[212:215], v191, s[84:85] offset:32
	global_load_dwordx4 v[216:219], v191, s[84:85] offset:48
	global_load_dwordx4 v[220:223], v191, s[84:85]
	global_load_dwordx4 v[224:227], v191, s[84:85] offset:16
	s_or_b64 exec, exec, s[12:13]
	v_cvt_pk_bf16_f32 v60, v60, v61
	v_cvt_pk_bf16_f32 v61, v62, v63
	v_cvt_pk_bf16_f32 v62, v56, v57
	v_cvt_pk_bf16_f32 v63, v58, v59
	v_cvt_pk_bf16_f32 v52, v52, v53
	v_cvt_pk_bf16_f32 v53, v54, v55
	v_cvt_pk_bf16_f32 v54, v48, v49
	v_cvt_pk_bf16_f32 v55, v50, v51
	v_cndmask_b32_e64 v174, v60, v52, s[6:7]
	v_cndmask_b32_e64 v175, v61, v53, s[6:7]
	v_cndmask_b32_e64 v176, v62, v54, s[6:7]
	v_cndmask_b32_e64 v177, v63, v55, s[6:7]
	v_mov_b32_dpp v178, v174 row_ror:8 row_mask:0xf bank_mask:0xf
	v_mov_b32_dpp v179, v175 row_ror:8 row_mask:0xf bank_mask:0xf
	v_mov_b32_dpp v180, v176 row_ror:8 row_mask:0xf bank_mask:0xf
	v_mov_b32_dpp v181, v177 row_ror:8 row_mask:0xf bank_mask:0xf
	v_cndmask_b32_e64 v52, v52, v178, s[6:7]
	v_cndmask_b32_e64 v60, v178, v60, s[6:7]
	v_cndmask_b32_e64 v53, v53, v179, s[6:7]
	v_cndmask_b32_e64 v61, v179, v61, s[6:7]
	v_cndmask_b32_e64 v54, v54, v180, s[6:7]
	v_cndmask_b32_e64 v62, v180, v62, s[6:7]
	v_cndmask_b32_e64 v55, v55, v181, s[6:7]
	v_cndmask_b32_e64 v63, v181, v63, s[6:7]
	v_lshl_add_u64 v[152:153], v[150:151], 0, s[50:51]
	v_lshl_add_u64 v[184:185], v[182:183], 0, s[50:51]
	global_store_dwordx4 v[152:153], v[60:63], off
	global_store_dwordx4 v[184:185], v[52:55], off
	s_add_u32 s50, s50, s11
	s_addc_u32 s51, s51, 0
	ds_bpermute_b32 v166, v156, v44
	ds_bpermute_b32 v167, v156, v45
	ds_bpermute_b32 v168, v156, v46
	ds_bpermute_b32 v169, v156, v47
	ds_bpermute_b32 v170, v156, v40
	ds_bpermute_b32 v171, v156, v41
	ds_bpermute_b32 v172, v156, v42
	ds_bpermute_b32 v173, v156, v43
	s_and_saveexec_b64 s[12:13], s[2:3]
	s_waitcnt vmcnt(14)
	v_pk_mul_f32 v[228:229], v[228:229], v[164:165] op_sel_hi:[1,0]
	v_pk_mul_f32 v[232:233], v[232:233], v[164:165] op_sel_hi:[1,0]
	v_pk_mul_f32 v[230:231], v[230:231], v[164:165] op_sel_hi:[1,0]
	v_pk_mul_f32 v[234:235], v[234:235], v[164:165] op_sel_hi:[1,0]
	s_waitcnt lgkmcnt(0)
	v_pk_mul_f32 v[166:167], v[228:229], v[166:167]
	v_pk_mul_f32 v[170:171], v[232:233], v[170:171]
	v_pk_mul_f32 v[168:169], v[230:231], v[168:169]
	v_pk_mul_f32 v[172:173], v[234:235], v[172:173]
	v_pk_fma_f32 v[44:45], v[44:45], v[236:237], v[166:167]
	v_pk_fma_f32 v[40:41], v[40:41], v[186:187], v[170:171]
	v_pk_fma_f32 v[46:47], v[46:47], v[238:239], v[168:169]
	v_pk_fma_f32 v[42:43], v[42:43], v[188:189], v[172:173]
	s_or_b64 exec, exec, s[12:13]
	v_cvt_pk_bf16_f32 v44, v44, v45
	v_cvt_pk_bf16_f32 v45, v46, v47
	v_cvt_pk_bf16_f32 v46, v40, v41
	v_cvt_pk_bf16_f32 v47, v42, v43
	v_cvt_pk_bf16_f32 v36, v36, v37
	v_cvt_pk_bf16_f32 v37, v38, v39
	v_cvt_pk_bf16_f32 v38, v32, v33
	v_cvt_pk_bf16_f32 v39, v34, v35
	v_cndmask_b32_e64 v174, v44, v36, s[6:7]
	v_cndmask_b32_e64 v175, v45, v37, s[6:7]
	v_cndmask_b32_e64 v176, v46, v38, s[6:7]
	v_cndmask_b32_e64 v177, v47, v39, s[6:7]
	v_mov_b32_dpp v178, v174 row_ror:8 row_mask:0xf bank_mask:0xf
	v_mov_b32_dpp v179, v175 row_ror:8 row_mask:0xf bank_mask:0xf
	v_mov_b32_dpp v180, v176 row_ror:8 row_mask:0xf bank_mask:0xf
	v_mov_b32_dpp v181, v177 row_ror:8 row_mask:0xf bank_mask:0xf
	v_cndmask_b32_e64 v36, v36, v178, s[6:7]
	v_cndmask_b32_e64 v44, v178, v44, s[6:7]
	v_cndmask_b32_e64 v37, v37, v179, s[6:7]
	v_cndmask_b32_e64 v45, v179, v45, s[6:7]
	v_cndmask_b32_e64 v38, v38, v180, s[6:7]
	v_cndmask_b32_e64 v46, v180, v46, s[6:7]
	v_cndmask_b32_e64 v39, v39, v181, s[6:7]
	v_cndmask_b32_e64 v47, v181, v47, s[6:7]
	v_lshl_add_u64 v[154:155], v[150:151], 0, s[50:51]
	v_lshl_add_u64 v[240:241], v[182:183], 0, s[50:51]
	global_store_dwordx4 v[154:155], v[44:47], off
	global_store_dwordx4 v[240:241], v[36:39], off
	s_add_u32 s50, s50, s11
	s_addc_u32 s51, s51, 0
	ds_bpermute_b32 v166, v156, v28
	ds_bpermute_b32 v167, v156, v29
	ds_bpermute_b32 v168, v156, v30
	ds_bpermute_b32 v169, v156, v31
	ds_bpermute_b32 v170, v156, v24
	ds_bpermute_b32 v171, v156, v25
	ds_bpermute_b32 v172, v156, v26
	ds_bpermute_b32 v173, v156, v27
	s_and_saveexec_b64 s[12:13], s[2:3]
	s_waitcnt vmcnt(10)
	v_pk_mul_f32 v[196:197], v[196:197], v[164:165] op_sel_hi:[1,0]
	v_pk_mul_f32 v[200:201], v[200:201], v[164:165] op_sel_hi:[1,0]
	v_pk_mul_f32 v[198:199], v[198:199], v[164:165] op_sel_hi:[1,0]
	v_pk_mul_f32 v[202:203], v[202:203], v[164:165] op_sel_hi:[1,0]
	s_waitcnt lgkmcnt(0)
	v_pk_mul_f32 v[166:167], v[196:197], v[166:167]
	v_pk_mul_f32 v[170:171], v[200:201], v[170:171]
	v_pk_mul_f32 v[168:169], v[198:199], v[168:169]
	v_pk_mul_f32 v[172:173], v[202:203], v[172:173]
	v_pk_fma_f32 v[28:29], v[28:29], v[204:205], v[166:167]
	v_pk_fma_f32 v[24:25], v[24:25], v[208:209], v[170:171]
	v_pk_fma_f32 v[30:31], v[30:31], v[206:207], v[168:169]
	v_pk_fma_f32 v[26:27], v[26:27], v[210:211], v[172:173]
	s_or_b64 exec, exec, s[12:13]
	v_cvt_pk_bf16_f32 v28, v28, v29
	v_cvt_pk_bf16_f32 v29, v30, v31
	v_cvt_pk_bf16_f32 v30, v24, v25
	v_cvt_pk_bf16_f32 v31, v26, v27
	v_cvt_pk_bf16_f32 v20, v20, v21
	v_cvt_pk_bf16_f32 v21, v22, v23
	v_cvt_pk_bf16_f32 v22, v16, v17
	v_cvt_pk_bf16_f32 v23, v18, v19
	v_cndmask_b32_e64 v174, v28, v20, s[6:7]
	v_cndmask_b32_e64 v175, v29, v21, s[6:7]
	v_cndmask_b32_e64 v176, v30, v22, s[6:7]
	v_cndmask_b32_e64 v177, v31, v23, s[6:7]
	v_mov_b32_dpp v178, v174 row_ror:8 row_mask:0xf bank_mask:0xf
	v_mov_b32_dpp v179, v175 row_ror:8 row_mask:0xf bank_mask:0xf
	v_mov_b32_dpp v180, v176 row_ror:8 row_mask:0xf bank_mask:0xf
	v_mov_b32_dpp v181, v177 row_ror:8 row_mask:0xf bank_mask:0xf
	v_cndmask_b32_e64 v20, v20, v178, s[6:7]
	v_cndmask_b32_e64 v28, v178, v28, s[6:7]
	v_cndmask_b32_e64 v21, v21, v179, s[6:7]
	v_cndmask_b32_e64 v29, v179, v29, s[6:7]
	v_cndmask_b32_e64 v22, v22, v180, s[6:7]
	v_cndmask_b32_e64 v30, v180, v30, s[6:7]
	v_cndmask_b32_e64 v23, v23, v181, s[6:7]
	v_cndmask_b32_e64 v31, v181, v31, s[6:7]
	v_lshl_add_u64 v[152:153], v[150:151], 0, s[50:51]
	v_lshl_add_u64 v[184:185], v[182:183], 0, s[50:51]
	global_store_dwordx4 v[152:153], v[28:31], off
	global_store_dwordx4 v[184:185], v[20:23], off
	s_add_u32 s50, s50, s11
	s_addc_u32 s51, s51, 0
	ds_bpermute_b32 v166, v156, v12
	ds_bpermute_b32 v167, v156, v13
	ds_bpermute_b32 v168, v156, v14
	ds_bpermute_b32 v169, v156, v15
	ds_bpermute_b32 v170, v156, v8
	ds_bpermute_b32 v171, v156, v9
	ds_bpermute_b32 v172, v156, v10
	ds_bpermute_b32 v173, v156, v11
	s_and_saveexec_b64 s[12:13], s[2:3]
	s_waitcnt vmcnt(6)
	v_pk_mul_f32 v[212:213], v[212:213], v[164:165] op_sel_hi:[1,0]
	v_pk_mul_f32 v[216:217], v[216:217], v[164:165] op_sel_hi:[1,0]
	v_pk_mul_f32 v[214:215], v[214:215], v[164:165] op_sel_hi:[1,0]
	v_pk_mul_f32 v[218:219], v[218:219], v[164:165] op_sel_hi:[1,0]
	s_waitcnt lgkmcnt(0)
	v_pk_mul_f32 v[166:167], v[212:213], v[166:167]
	v_pk_mul_f32 v[170:171], v[216:217], v[170:171]
	v_pk_mul_f32 v[168:169], v[214:215], v[168:169]
	v_pk_mul_f32 v[172:173], v[218:219], v[172:173]
	v_pk_fma_f32 v[12:13], v[12:13], v[220:221], v[166:167]
	v_pk_fma_f32 v[8:9], v[8:9], v[224:225], v[170:171]
	v_pk_fma_f32 v[14:15], v[14:15], v[222:223], v[168:169]
	v_pk_fma_f32 v[10:11], v[10:11], v[226:227], v[172:173]
	s_or_b64 exec, exec, s[12:13]
	v_cvt_pk_bf16_f32 v12, v12, v13
	v_cvt_pk_bf16_f32 v13, v14, v15
	v_cvt_pk_bf16_f32 v14, v8, v9
	v_cvt_pk_bf16_f32 v15, v10, v11
	v_cvt_pk_bf16_f32 v4, v4, v5
	v_cvt_pk_bf16_f32 v5, v6, v7
	v_cvt_pk_bf16_f32 v6, v0, v1
	v_cvt_pk_bf16_f32 v7, v2, v3
	v_cndmask_b32_e64 v174, v12, v4, s[6:7]
	v_cndmask_b32_e64 v175, v13, v5, s[6:7]
	v_cndmask_b32_e64 v176, v14, v6, s[6:7]
	v_cndmask_b32_e64 v177, v15, v7, s[6:7]
	v_mov_b32_dpp v178, v174 row_ror:8 row_mask:0xf bank_mask:0xf
	v_mov_b32_dpp v179, v175 row_ror:8 row_mask:0xf bank_mask:0xf
	v_mov_b32_dpp v180, v176 row_ror:8 row_mask:0xf bank_mask:0xf
	v_mov_b32_dpp v181, v177 row_ror:8 row_mask:0xf bank_mask:0xf
	v_cndmask_b32_e64 v4, v4, v178, s[6:7]
	v_cndmask_b32_e64 v12, v178, v12, s[6:7]
	v_cndmask_b32_e64 v5, v5, v179, s[6:7]
	v_cndmask_b32_e64 v13, v179, v13, s[6:7]
	v_cndmask_b32_e64 v6, v6, v180, s[6:7]
	v_cndmask_b32_e64 v14, v180, v14, s[6:7]
	v_cndmask_b32_e64 v7, v7, v181, s[6:7]
	v_cndmask_b32_e64 v15, v181, v15, s[6:7]
	v_lshl_add_u64 v[154:155], v[150:151], 0, s[50:51]
	v_lshl_add_u64 v[240:241], v[182:183], 0, s[50:51]
	global_store_dwordx4 v[154:155], v[12:15], off
	global_store_dwordx4 v[240:241], v[4:7], off
	s_branch .LBB0_174
